# v6 + scanner blocks skip the four empty queue grabs after their scan unit when one coherent load shows all P3 queues exhausted
# baseline (speedup 1.0000x reference)
.LBB0_468:
	s_mov_b32 s32, 0
	v_writelane_b32 v246, s52, 30
	s_nop 1
	v_writelane_b32 v246, s53, 31
	v_writelane_b32 v246, s29, 32
	v_writelane_b32 v246, s26, 33
	s_nop 1
	v_writelane_b32 v246, s27, 34
	v_writelane_b32 v246, s34, 35
	s_nop 1
	v_writelane_b32 v246, s35, 36
	v_writelane_b32 v246, s30, 37
	s_nop 1
	v_writelane_b32 v246, s31, 38
	s_or_b64 exec, exec, s[0:1]
	v_lshrrev_b32_e32 v155, 2, v130
	s_cmp_eq_u32 s33, 0
	s_waitcnt lgkmcnt(0)
	v_bfe_u32 v0, v130, 4, 2
	v_and_b32_e32 v1, 0xf0, v155
	s_cselect_b64 s[0:1], -1, 0
	v_or_b32_e32 v85, v1, v137
	v_lshlrev_b32_e32 v80, 2, v0
	v_writelane_b32 v246, s0, 39
	v_add_u32_e32 v2, 0x80, v85
	v_or_b32_e32 v120, v80, v1
	v_writelane_b32 v246, s1, 40
	s_cmp_lg_u32 s33, 0
	v_cmp_ge_u32_e32 vcc, v80, v137
	v_cmp_le_u32_e64 s[0:1], v120, v2
	v_or_b32_e32 v1, 1, v120
	s_cselect_b64 s[58:59], -1, 0
	s_and_b64 s[20:21], vcc, s[0:1]
	v_cmp_ge_u32_e32 vcc, v1, v85
	v_cmp_lt_u32_e64 s[0:1], v120, v2
	s_and_b64 s[0:1], vcc, s[0:1]
	v_or_b32_e32 v121, 2, v120
	v_writelane_b32 v248, s0, 58
	v_cmp_ge_u32_e32 vcc, v121, v85
	v_or_b32_e32 v122, 3, v120
	v_writelane_b32 v248, s1, 59
	v_cmp_le_u32_e64 s[0:1], v121, v2
	s_and_b64 s[0:1], vcc, s[0:1]
	v_cmp_ge_u32_e32 vcc, v122, v85
	v_writelane_b32 v246, s0, 10
	v_add_u32_e32 v123, 16, v120
	v_add_u32_e32 v1, 17, v120
	v_writelane_b32 v246, s1, 11
	v_cmp_le_u32_e64 s[0:1], v122, v2
	s_and_b64 s[0:1], vcc, s[0:1]
	v_cmp_ge_u32_e32 vcc, v123, v85
	v_writelane_b32 v246, s0, 20
	v_or_b32_e32 v124, 2, v123
	v_or_b32_e32 v125, 3, v123
	v_writelane_b32 v246, s1, 21
	v_cmp_le_u32_e64 s[0:1], v123, v2
	s_and_b64 s[0:1], vcc, s[0:1]
	v_cmp_ge_u32_e32 vcc, v1, v85
	v_writelane_b32 v246, s0, 12
	v_add_u32_e32 v126, 32, v120
	v_add_u32_e32 v1, 33, v120
	v_writelane_b32 v246, s1, 13
	v_cmp_lt_u32_e64 s[0:1], v123, v2
	s_and_b64 s[0:1], vcc, s[0:1]
	v_cmp_ge_u32_e32 vcc, v124, v85
	v_writelane_b32 v246, s0, 6
	v_or_b32_e32 v127, 2, v126
	v_or_b32_e32 v142, 3, v126
	v_writelane_b32 v246, s1, 7
	v_cmp_le_u32_e64 s[0:1], v124, v2
	s_and_b64 s[0:1], vcc, s[0:1]
	v_cmp_ge_u32_e32 vcc, v125, v85
	v_writelane_b32 v246, s0, 8
	v_add_u32_e32 v143, 48, v120
	v_or_b32_e32 v144, 2, v143
	v_writelane_b32 v246, s1, 9
	v_cmp_le_u32_e64 s[0:1], v125, v2
	s_and_b64 s[0:1], vcc, s[0:1]
	v_cmp_ge_u32_e32 vcc, v126, v85
	v_writelane_b32 v246, s0, 16
	v_or_b32_e32 v145, 3, v143
	v_add_u32_e32 v146, 64, v120
	v_writelane_b32 v246, s1, 17
	v_cmp_le_u32_e64 s[0:1], v126, v2
	s_and_b64 s[0:1], vcc, s[0:1]
	v_cmp_ge_u32_e32 vcc, v1, v85
	v_writelane_b32 v246, s0, 14
	v_add_u32_e32 v1, 49, v120
	v_or_b32_e32 v147, 2, v146
	v_writelane_b32 v246, s1, 15
	v_cmp_lt_u32_e64 s[0:1], v126, v2
	s_and_b64 s[0:1], vcc, s[0:1]
	v_cmp_ge_u32_e32 vcc, v127, v85
	v_writelane_b32 v246, s0, 18
	v_or_b32_e32 v148, 3, v146
	v_add_u32_e32 v149, 0x50, v120
	v_writelane_b32 v246, s1, 19
	v_cmp_le_u32_e64 s[0:1], v127, v2
	s_and_b64 s[0:1], vcc, s[0:1]
	v_cmp_ge_u32_e32 vcc, v142, v85
	v_writelane_b32 v246, s0, 24
	v_or_b32_e32 v150, 2, v149
	v_or_b32_e32 v151, 3, v149
	v_writelane_b32 v246, s1, 25
	v_cmp_le_u32_e64 s[0:1], v142, v2
	s_and_b64 s[0:1], vcc, s[0:1]
	v_cmp_ge_u32_e32 vcc, v143, v85
	v_writelane_b32 v246, s0, 22
	v_add_u32_e32 v152, 0x60, v120
	v_or_b32_e32 v153, 2, v152
	v_writelane_b32 v246, s1, 23
	v_cmp_le_u32_e64 s[0:1], v143, v2
	s_and_b64 s[0:1], vcc, s[0:1]
	v_cmp_ge_u32_e32 vcc, v1, v85
	v_writelane_b32 v246, s0, 2
	v_add_u32_e32 v1, 0x41, v120
	v_or_b32_e32 v154, 3, v152
	v_writelane_b32 v246, s1, 3
	v_cmp_lt_u32_e64 s[0:1], v143, v2
	s_and_b64 s[0:1], vcc, s[0:1]
	v_cmp_ge_u32_e32 vcc, v144, v85
	v_writelane_b32 v246, s0, 0
	v_add_u32_e32 v160, 0x70, v120
	v_or_b32_e32 v161, 2, v160
	v_writelane_b32 v246, s1, 1
	v_cmp_le_u32_e64 s[0:1], v144, v2
	s_and_b64 s[0:1], vcc, s[0:1]
	v_cmp_ge_u32_e32 vcc, v145, v85
	v_writelane_b32 v246, s0, 4
	v_or_b32_e32 v162, 3, v160
	v_add_u32_e32 v3, 0x81, v120
	v_writelane_b32 v246, s1, 5
	v_cmp_le_u32_e64 s[0:1], v145, v2
	s_and_b64 s[0:1], vcc, s[0:1]
	v_cmp_ge_u32_e32 vcc, v146, v85
	v_writelane_b32 v248, s0, 60
	v_lshlrev_b32_e32 v159, 7, v136
	v_lshlrev_b32_e32 v40, 5, v137
	v_writelane_b32 v248, s1, 61
	v_cmp_le_u32_e64 s[0:1], v146, v2
	s_and_b64 s[0:1], vcc, s[0:1]
	v_cmp_ge_u32_e32 vcc, v1, v85
	v_writelane_b32 v248, s0, 62
	v_add_u32_e32 v1, 0x51, v120
	v_readlane_b32 s36, v247, 13
	v_writelane_b32 v248, s1, 63
	v_cmp_lt_u32_e64 s[0:1], v146, v2
	s_and_b64 s[0:1], vcc, s[0:1]
	v_cmp_ge_u32_e32 vcc, v147, v85
	v_writelane_b32 v248, s0, 13
	v_readlane_b32 s48, v247, 25
	v_readlane_b32 s49, v247, 26
	v_writelane_b32 v248, s1, 14
	v_cmp_le_u32_e64 s[0:1], v147, v2
	s_and_b64 s[0:1], vcc, s[0:1]
	v_cmp_ge_u32_e32 vcc, v148, v85
	v_writelane_b32 v248, s0, 56
	v_readlane_b32 s80, v247, 45
	v_readlane_b32 s81, v247, 46
	v_writelane_b32 v248, s1, 57
	v_cmp_le_u32_e64 s[0:1], v148, v2
	s_and_b64 s[0:1], vcc, s[0:1]
	v_cmp_ge_u32_e32 vcc, v149, v85
	v_writelane_b32 v246, s0, 41
	v_readlane_b32 s60, v248, 16
	v_readlane_b32 s66, v248, 22
	v_writelane_b32 v246, s1, 42
	v_cmp_le_u32_e64 s[0:1], v149, v2
	s_and_b64 s[0:1], vcc, s[0:1]
	v_cmp_ge_u32_e32 vcc, v1, v85
	v_writelane_b32 v246, s0, 43
	v_add_u32_e32 v1, 0x61, v120
	v_readlane_b32 s74, v248, 30
	v_writelane_b32 v246, s1, 44
	v_cmp_lt_u32_e64 s[0:1], v149, v2
	s_and_b64 s[0:1], vcc, s[0:1]
	v_cmp_ge_u32_e32 vcc, v150, v85
	v_writelane_b32 v246, s0, 45
	v_readlane_b32 s67, v248, 23
	v_readlane_b32 s75, v248, 31
	v_writelane_b32 v246, s1, 46
	v_cmp_le_u32_e64 s[0:1], v150, v2
	s_and_b64 s[56:57], vcc, s[0:1]
	v_cmp_ge_u32_e32 vcc, v151, v85
	v_cmp_le_u32_e64 s[0:1], v151, v2
	s_and_b64 s[78:79], vcc, s[0:1]
	v_cmp_ge_u32_e32 vcc, v152, v85
	v_cmp_le_u32_e64 s[0:1], v152, v2
	s_and_b64 s[4:5], vcc, s[0:1]
	v_cmp_ge_u32_e32 vcc, v1, v85
	v_cmp_lt_u32_e64 s[0:1], v152, v2
	s_and_b64 s[6:7], vcc, s[0:1]
	v_cmp_ge_u32_e32 vcc, v153, v85
	v_cmp_le_u32_e64 s[0:1], v153, v2
	s_and_b64 s[76:77], vcc, s[0:1]
	v_cmp_ge_u32_e32 vcc, v154, v85
	v_cmp_le_u32_e64 s[0:1], v154, v2
	s_and_b64 s[2:3], vcc, s[0:1]
	v_cmp_ge_u32_e32 vcc, v160, v85
	v_cmp_le_u32_e64 s[0:1], v160, v2
	v_add_u32_e32 v1, 0x71, v120
	s_and_b64 s[54:55], vcc, s[0:1]
	v_cmp_ge_u32_e32 vcc, v1, v85
	v_cmp_lt_u32_e64 s[0:1], v160, v2
	s_and_b64 s[52:53], vcc, s[0:1]
	v_cmp_ge_u32_e32 vcc, v161, v85
	v_cmp_le_u32_e64 s[0:1], v161, v2
	s_and_b64 s[30:31], vcc, s[0:1]
	v_cmp_ge_u32_e32 vcc, v162, v85
	v_cmp_le_u32_e64 s[0:1], v162, v2
	v_add_u32_e32 v1, 0x80, v120
	s_and_b64 s[34:35], vcc, s[0:1]
	v_cmp_ge_u32_e32 vcc, v1, v85
	v_cmp_le_u32_e64 s[0:1], v1, v2
	s_and_b64 s[10:11], vcc, s[0:1]
	v_cmp_ge_u32_e32 vcc, v3, v85
	v_cmp_lt_u32_e64 s[0:1], v1, v2
	v_or_b32_e32 v3, 2, v1
	s_and_b64 s[12:13], vcc, s[0:1]
	v_cmp_ge_u32_e32 vcc, v3, v85
	v_cmp_le_u32_e64 s[0:1], v3, v2
	v_or_b32_e32 v1, 3, v1
	s_and_b64 s[14:15], vcc, s[0:1]
	v_cmp_ge_u32_e32 vcc, v1, v85
	v_cmp_le_u32_e64 s[0:1], v1, v2
	v_lshlrev_b32_e32 v1, 8, v136
	s_and_b64 s[16:17], vcc, s[0:1]
	v_sub_u32_e32 v5, v1, v159
	s_movk_i32 s0, 0xff84
	v_mad_i32_i24 v163, v136, s0, v5
	v_mul_u32_u24_e32 v2, 0x10c, v136
	v_add3_u32 v2, v163, v2, v40
	v_add_u32_e32 v3, 0x9540, v2
	v_sub_u32_e32 v2, v2, v159
	v_add_u32_e32 v4, 0x8cc0, v2
	v_cmp_gt_u32_e32 vcc, 8, v137
	v_add_u32_e32 v2, 0x8440, v2
	s_mov_b64 s[0:1], 0x1000
	v_cndmask_b32_e32 v3, v3, v4, vcc
	v_cmp_gt_u32_e32 vcc, 4, v137
	s_add_u32 s66, s74, 0x2000
	s_addc_u32 s67, s75, 0
	v_cndmask_b32_e32 v164, v3, v2, vcc
	v_lshlrev_b64 v[2:3], 2, v[130:131]
	v_lshl_add_u64 v[44:45], s[48:49], 0, v[2:3]
	v_lshl_add_u64 v[46:47], v[44:45], 0, s[0:1]
	s_mov_b64 s[0:1], 0x2000
	v_lshl_add_u64 v[48:49], v[44:45], 0, s[0:1]
	s_mov_b64 s[0:1], 0x3000
	v_lshl_add_u64 v[62:63], s[80:81], 0, v[2:3]
	s_add_u32 s80, s74, 0x2004
	v_readlane_b32 s37, v247, 14
	v_readlane_b32 s38, v247, 15
	v_readlane_b32 s39, v247, 16
	v_readlane_b32 s40, v247, 17
	v_readlane_b32 s41, v247, 18
	v_readlane_b32 s42, v247, 19
	v_readlane_b32 s43, v247, 20
	v_readlane_b32 s44, v247, 21
	v_readlane_b32 s45, v247, 22
	v_readlane_b32 s46, v247, 23
	v_readlane_b32 s47, v247, 24
	v_readlane_b32 s50, v247, 27
	v_readlane_b32 s51, v247, 28
	v_lshl_add_u64 v[50:51], v[44:45], 0, s[0:1]
	s_movk_i32 s0, 0x104
	v_lshlrev_b32_e32 v6, 2, v129
	s_movk_i32 s33, 0x90
	v_readlane_b32 s82, v247, 47
	s_addc_u32 s81, s75, 0
	v_lshlrev_b32_e32 v4, 2, v128
	v_mad_u32_u24 v83, v128, s0, v6
	v_mul_lo_u32 v6, v85, s33
	v_readlane_b32 s36, v247, 29
	v_readlane_b32 s83, v247, 48
	s_add_u32 s82, s74, 0x200c
	v_mad_u32_u24 v81, v129, s0, v4
	v_lshl_add_u32 v7, v85, 7, v6
	s_movk_i32 s0, 0xfef4
	v_lshlrev_b32_e32 v9, 4, v0
	v_readlane_b32 s37, v247, 30
	v_readlane_b32 s38, v247, 31
	v_readlane_b32 s39, v247, 32
	v_readlane_b32 s40, v247, 33
	v_readlane_b32 s41, v247, 34
	v_readlane_b32 s42, v247, 35
	v_readlane_b32 s43, v247, 36
	v_readlane_b32 s44, v247, 37
	v_readlane_b32 s45, v247, 38
	v_readlane_b32 s46, v247, 39
	v_readlane_b32 s47, v247, 40
	v_readlane_b32 s48, v247, 41
	v_readlane_b32 s49, v247, 42
	v_readlane_b32 s50, v247, 43
	v_readlane_b32 s51, v247, 44
	s_addc_u32 s83, s75, 0
	v_mov_b32_e32 v41, 0
	v_mad_i32_i24 v8, v85, s0, v7
	v_add_u32_e32 v167, v6, v9
	v_mul_u32_u24_e32 v6, 0x190, v137
	v_and_b32_e32 v157, 3, v130
	v_lshlrev_b32_e32 v84, 4, v137
	v_lshl_add_u64 v[54:55], s[44:45], 0, v[2:3]
	v_lshl_add_u64 v[56:57], s[46:47], 0, v[2:3]
	v_lshl_add_u64 v[58:59], s[48:49], 0, v[2:3]
	v_lshl_add_u64 v[60:61], s[50:51], 0, v[2:3]
	v_readlane_b32 s36, v248, 40
	s_add_u32 s0, s74, 0x2008
	v_lshl_add_u64 v[42:43], s[18:19], 0, v[40:41]
	v_lshl_add_u32 v168, v120, 1, v6
	v_lshlrev_b32_e32 v78, 5, v157
	v_mul_u32_u24_e32 v10, 0x90, v155
	v_lshlrev_b32_e32 v11, 7, v155
	v_lshlrev_b32_e32 v6, 6, v157
	v_or_b32_e32 v171, v1, v84
	v_lshlrev_b32_e32 v1, 7, v137
	v_add_u32_e32 v197, v7, v9
	v_mov_b32_e32 v79, v41
	v_readlane_b32 s37, v248, 41
	v_readlane_b32 s38, v248, 42
	v_readlane_b32 s39, v248, 43
	v_readlane_b32 s40, v248, 44
	v_readlane_b32 s41, v248, 45
	v_readlane_b32 s42, v248, 46
	v_readlane_b32 s43, v248, 47
	v_readlane_b32 s44, v248, 48
	v_readlane_b32 s45, v248, 49
	v_readlane_b32 s46, v248, 50
	v_readlane_b32 s47, v248, 51
	v_readlane_b32 s48, v248, 52
	v_readlane_b32 s49, v248, 53
	v_readlane_b32 s50, v248, 54
	v_readlane_b32 s51, v248, 55
	v_mov_b32_e32 v7, v41
	v_lshlrev_b32_e32 v40, 1, v128
	s_addc_u32 s1, s75, 0
	v_add3_u32 v170, v10, v11, v6
	v_add_u32_e32 v10, v84, v1
	v_lshlrev_b32_e32 v11, 1, v85
	v_lshlrev_b32_e32 v158, 8, v137
	v_lshl_add_u64 v[64:65], s[44:45], 0, v[78:79]
	v_lshl_add_u64 v[66:67], s[46:47], 0, v[78:79]
	v_lshl_add_u64 v[68:69], s[48:49], 0, v[6:7]
	v_readlane_b32 s64, v248, 20
	v_readlane_b32 s65, v248, 21
	v_lshl_add_u64 v[26:27], s[38:39], 0, v[40:41]
	v_lshl_add_u64 v[30:31], s[36:37], 0, v[40:41]
	v_readlane_b32 s36, v247, 61
	v_writelane_b32 v246, s0, 47
	v_and_b32_e32 v52, 48, v177
	v_add_u32_e32 v1, v10, v1
	v_sub_u32_e32 v11, v8, v11
	v_sub_u32_e32 v12, 0, v158
	v_and_b32_e32 v193, 0x3f8, v130
	v_lshl_or_b32 v194, v137, 3, v5
	v_readlane_b32 s86, v247, 51
	v_readlane_b32 s87, v247, 52
	v_readlane_b32 s88, v247, 53
	v_readlane_b32 s89, v247, 54
	v_readlane_b32 s90, v247, 55
	v_readlane_b32 s91, v247, 56
	v_readlane_b32 s94, v247, 59
	v_readlane_b32 s95, v247, 60
	v_readlane_b32 s68, v248, 24
	v_readlane_b32 s69, v248, 25
	v_readlane_b32 s70, v248, 26
	v_readlane_b32 s71, v248, 27
	v_readlane_b32 s72, v248, 28
	v_readlane_b32 s73, v248, 29
	v_mov_b32_e32 v5, v41
	v_readlane_b32 s48, v248, 9
	v_readlane_b32 s49, v248, 10
	v_readlane_b32 s50, v248, 11
	v_readlane_b32 s51, v248, 12
	v_writelane_b32 v246, s1, 48
	s_mov_b64 s[0:1], -1
	v_readlane_b32 s64, v247, 10
	v_or_b32_e32 v165, 0xffffff00, v155
	v_mul_u32_u24_e32 v166, 0x190, v52
	v_lshlrev_b32_e32 v82, 3, v0
	v_and_b32_e32 v53, 60, v136
	v_lshlrev_b32_e32 v74, 4, v128
	v_lshlrev_b32_e32 v72, 3, v128
	v_mov_b32_e32 v73, v41
	v_lshlrev_b32_e32 v156, 2, v137
	v_mad_u32_u24 v169, v155, s33, v78
	v_lshlrev_b32_e32 v177, 5, v175
	v_add_u32_e32 v195, v10, v9
	v_add_u32_e32 v196, v1, v9
	v_lshl_add_u32 v198, v0, 10, v8
	v_lshl_add_u32 v199, v0, 9, v11
	s_mov_b64 s[70:71], s[20:21]
	v_lshl_add_u64 v[24:25], s[94:95], 0, v[4:5]
	v_lshl_add_u64 v[28:29], s[90:91], 0, v[4:5]
	v_lshl_add_u64 v[32:33], s[88:89], 0, v[4:5]
	v_lshl_add_u64 v[34:35], s[50:51], 0, v[40:41]
	v_lshl_add_u64 v[36:37], s[86:87], 0, v[4:5]
	v_lshl_add_u64 v[38:39], s[48:49], 0, v[40:41]
	v_add_u32_e32 v79, 0x5100, v193
	v_subrev_u32_e32 v200, 64, v155
	v_mov_b32_e32 v201, 0x260
	v_mov_b32_e32 v202, 0x3a27c5ac
	v_add_u32_e32 v203, 64, v140
	v_mov_b32_e32 v204, 0x1800
	v_add_u32_e32 v205, v1, v12
	v_mov_b32_e32 v206, 0xf149f2ca
	v_mbcnt_hi_u32_b32 v75, -1, v192
	v_mov_b32_e32 v192, 0x41b17218
	s_movk_i32 s90, 0x1800
	s_movk_i32 s91, 0x7fff
	s_mov_b32 s68, 0x800000
	s_movk_i32 s69, 0x1200
	s_mov_b32 s72, 0x7060302
	s_mov_b32 s73, 0x40c00000
	s_mov_b32 s29, 0
	v_cmp_eq_u32_e64 s[18:19], 0, v0
	v_cmp_eq_u32_e64 s[8:9], 0, v128
	v_cmp_gt_u32_e64 s[20:21], 64, v130
	v_cmp_lt_u32_e64 s[22:23], 15, v130
	v_cmp_eq_u32_e64 s[24:25], 0, v137
	v_cmp_eq_u32_e64 s[26:27], 0, v175
	v_writelane_b32 v246, s0, 49
	v_readlane_b32 s65, v247, 11
	s_barrier
	v_readlane_b32 s84, v247, 49
	v_readlane_b32 s85, v247, 50
	v_readlane_b32 s92, v247, 57
	v_readlane_b32 s93, v247, 58
	v_readlane_b32 s61, v248, 17
	v_readlane_b32 s62, v248, 18
	v_readlane_b32 s63, v248, 19
	v_readlane_b32 s37, v247, 62
	v_readlane_b32 s38, v247, 63
	v_readlane_b32 s39, v248, 0
	v_readlane_b32 s40, v248, 1
	v_readlane_b32 s41, v248, 2
	v_readlane_b32 s42, v248, 3
	v_readlane_b32 s43, v248, 4
	v_readlane_b32 s44, v248, 5
	v_readlane_b32 s45, v248, 6
	v_readlane_b32 s46, v248, 7
	v_readlane_b32 s47, v248, 8
	v_writelane_b32 v246, s1, 50
	s_branch .LBB0_470

.LBB0_472:
	s_setprio 0
	s_and_saveexec_b64 s[60:61], s[64:65]
	s_cbranch_execz .Lq_w
	global_load_dwordx4 v[8:11], v41, s[66:67] sc1
	s_waitcnt vmcnt(0)
	v_readfirstlane_b32 s28, v8
	v_readfirstlane_b32 s58, v9
	v_readfirstlane_b32 s59, v10
	v_readfirstlane_b32 s62, v11
	s_mov_b32 s63, 0
	s_nop 3
	s_cmpk_lt_u32 s28, 0x100
	s_cbranch_scc1 .Lq_st
	s_cmpk_lt_u32 s58, 0x1800
	s_cbranch_scc1 .Lq_st
	s_cmpk_lt_u32 s59, 0x440
	s_cbranch_scc1 .Lq_st
	s_cmpk_lt_u32 s62, 0x800
	s_cbranch_scc1 .Lq_st
	s_mov_b32 s63, 1
.Lq_st:
	v_mov_b32_e32 v8, s63
	ds_write_b32 v41, v8 offset:4
.Lq_w:
	s_or_b64 exec, exec, s[60:61]
	s_waitcnt lgkmcnt(0)
	s_barrier
	ds_read_b32 v8, v41 offset:4
	s_waitcnt lgkmcnt(0)
	v_readfirstlane_b32 s32, v8
	s_nop 3
	s_cmp_lg_u32 s32, 0
	s_cbranch_scc1 .LBB0_555
	s_mov_b64 s[0:1], 0

.LBB0_555:
	v_readlane_b32 s52, v248, 16
	v_readlane_b32 s60, v248, 24
	v_readlane_b32 s61, v248, 25
	v_readlane_b32 s66, v248, 30
	v_readlane_b32 s67, v248, 31
	v_readlane_b32 s58, v248, 22
	v_readlane_b32 s59, v248, 23
	v_readlane_b32 s62, v248, 26
	v_readlane_b32 s63, v248, 27
	v_readlane_b32 s60, v247, 10
	v_readlane_b32 s68, v248, 32
	v_readlane_b32 s66, v246, 33
	s_mov_b32 s1, 0
	s_waitcnt vmcnt(6)
	v_mov_b32_e32 v1, 0
	s_movk_i32 s10, 0x440
	s_movk_i32 s11, 0x7fff
	v_readlane_b32 s53, v248, 17
	v_readlane_b32 s54, v248, 18
	v_readlane_b32 s55, v248, 19
	v_readlane_b32 s56, v248, 20
	v_readlane_b32 s57, v248, 21
	v_readlane_b32 s64, v248, 28
	v_readlane_b32 s65, v248, 29
	v_readlane_b32 s61, v247, 11
	v_readlane_b32 s69, v248, 33
	v_readlane_b32 s70, v248, 34
	v_readlane_b32 s71, v248, 35
	v_readlane_b32 s72, v248, 36
	v_readlane_b32 s73, v248, 37
	v_readlane_b32 s74, v248, 38
	v_readlane_b32 s75, v248, 39
	v_readlane_b32 s58, v248, 15
	v_readlane_b32 s62, v246, 37
	v_readlane_b32 s67, v246, 34
	v_readlane_b32 s59, v246, 32
	v_readlane_b32 s63, v246, 38
	s_cmp_lg_u32 s32, 0
	s_cbranch_scc1 .LBB0_575
	s_branch .LBB0_558

.LBB0_575:
	v_and_b32_e32 v79, 64, v75
	v_mov_b32_e32 v77, 0
	s_movk_i32 s10, 0x7ff
	v_xor_b32_e32 v81, 16, v75
	v_add_u32_e32 v83, 64, v79
	v_xor_b32_e32 v154, 32, v75
	s_mov_b32 s11, 0x40c00000
	v_lshlrev_b32_e32 v76, 2, v74
	s_cmp_lg_u32 s32, 0
	s_cbranch_scc1 .LBB0_591
	s_branch .LBB0_578
